# prompt attention: the 8 V-tile row loads of an item issued together into spare VGPR quads and written to LDS behind counted waits (was load, vmcnt(0), 8 ds_write_b16, eight times)
# speedup vs baseline: 1.0231x; 1.0231x over previous
; __device__ void attn_prompt_item(const P& p, int item, u16* vT) {
;     ...
;   __syncthreads();
; #pragma unroll
;   for (int i = 0; i < 8; ++i) {
;     int id = tid + i * 256, j = id >> 3, c = id & 7;
;     int pos = (n - 1) * 128 + j;
;     BF8 t; t.q = make_uint4(0, 0, 0, 0);
;     if (pos >= 0) t.q = *(const uint4*)(p_proj + ((size_t)b * 8192 + pos) * INW + 640 + kvh * 64 + c * 8);
; #pragma unroll
;     for (int e = 0; e < 8; ++e) vT[(c * 8 + e) * VS + j] = (u16)(t.u[e >> 1] >> ((e & 1) * 16));
;   }
.LBB0_325:
	s_bfe_u32 s6, s55, 0x60003
	v_mov_b32_e32 v8, v220
	s_ashr_i32 s0, s55, 9
	s_lshl_b32 s5, s6, 7
	s_add_i32 s7, s5, 0xffffff80
	v_lshlrev_b32_e32 v0, 3, v8
	s_ashr_i32 s1, s0, 31
	v_ashrrev_i32_e32 v5, 3, v8
	v_and_b32_e32 v4, 56, v0
	s_lshl_b64 s[38:39], s[0:1], 13
	s_lshl_b32 s0, s55, 4
	v_add_u32_e32 v24, s7, v5
	s_and_b32 s4, s0, 64
	v_cmp_lt_i32_e32 vcc, -1, v24
	v_lshlrev_b32_e32 v6, 1, v4
	v_mov_b32_e32 v0, 0
	v_mov_b32_e32 v1, 0
	v_mov_b32_e32 v2, 0
	v_mov_b32_e32 v3, 0
	s_waitcnt vmcnt(0) lgkmcnt(0)
	s_barrier
	v_mov_b32_e32 v194, 0
	v_mov_b32_e32 v195, 0
	v_mov_b32_e32 v196, 0
	v_mov_b32_e32 v197, 0
	s_and_saveexec_b64 s[0:1], vcc
	s_cbranch_execz .LBB0_327
	v_readlane_b32 s8, v228, 2
	v_readlane_b32 s14, v228, 8
	v_readlane_b32 s15, v228, 9
	v_lshl_add_u64 v[0:1], s[38:39], 0, v[24:25]
	v_readlane_b32 s9, v228, 3
	v_mov_b64_e32 v[2:3], s[14:15]
	v_mad_u64_u32 v[2:3], s[8:9], v0, s60, v[2:3]
	v_mad_i32_i24 v3, v1, s60, v3
	s_lshl_b32 s40, s4, 1
	v_lshl_add_u64 v[0:1], v[2:3], 0, s[40:41]
	v_mov_b32_e32 v7, v25
	v_lshl_add_u64 v[0:1], v[0:1], 0, v[6:7]
	v_add_co_u32_e32 v0, vcc, 0x8140000, v0
	v_readlane_b32 s10, v228, 4
	s_nop 0
	v_addc_co_u32_e32 v1, vcc, 0, v1, vcc
	global_load_dwordx4 v[194:197], v[0:1], off offset:1280
	v_readlane_b32 s11, v228, 5
	v_readlane_b32 s12, v228, 6
	v_readlane_b32 s13, v228, 7
.LBB0_327:
	s_or_b64 exec, exec, s[0:1]
	v_mul_u32_u24_e32 v9, 0x230, v4
	v_lshl_add_u32 v4, v5, 1, v9
	v_mov_b32_e32 v226, v4


; __device__ void attn_prompt_item(const P& p, int item, u16* vT) {
;     ...
;   for (int i = 0; i < 8; ++i) {
;     int id = tid + i * 256, j = id >> 3, c = id & 7;
;     int pos = (n - 1) * 128 + j;
;     BF8 t; t.q = make_uint4(0, 0, 0, 0);
;     if (pos >= 0) t.q = *(const uint4*)(p_proj + ((size_t)b * 8192 + pos) * INW + 640 + kvh * 64 + c * 8);
; #pragma unroll
;     for (int e = 0; e < 8; ++e) vT[(c * 8 + e) * VS + j] = (u16)(t.u[e >> 1] >> ((e & 1) * 16));
;   }
	v_add_u32_e32 v0, 0x100, v8
	v_ashrrev_i32_e32 v1, 3, v0
	v_add_u32_e32 v24, s7, v1
	v_cmp_lt_i32_e32 vcc, -1, v24
	v_mov_b32_e32 v0, 0
	v_mov_b32_e32 v2, 0
	v_mov_b32_e32 v3, 0
	v_mov_b32_e32 v4, 0
	v_mov_b32_e32 v5, 0
	v_mov_b32_e32 v198, 0
	v_mov_b32_e32 v199, 0
	v_mov_b32_e32 v200, 0
	v_mov_b32_e32 v201, 0
	s_and_saveexec_b64 s[0:1], vcc
	s_cbranch_execz .LBB0_329
	v_lshl_add_u64 v[2:3], s[38:39], 0, v[24:25]
	v_mad_u64_u32 v[4:5], s[8:9], v2, s60, v[26:27]
	v_mad_i32_i24 v5, v3, s60, v5
	s_lshl_b32 s40, s4, 1
	v_lshl_add_u64 v[2:3], v[4:5], 0, s[40:41]
	v_mov_b32_e32 v7, v25
	v_lshl_add_u64 v[2:3], v[2:3], 0, v[6:7]
	v_add_co_u32_e32 v2, vcc, 0x8140000, v2
	s_nop 1
	v_addc_co_u32_e32 v3, vcc, 0, v3, vcc
	global_load_dwordx4 v[198:201], v[2:3], off offset:1280
.LBB0_329:
	s_or_b64 exec, exec, s[0:1]
	v_lshl_add_u32 v1, v1, 1, v9


; __device__ void attn_prompt_item(const P& p, int item, u16* vT) {
;     ...
;   for (int i = 0; i < 8; ++i) {
;     int id = tid + i * 256, j = id >> 3, c = id & 7;
;     int pos = (n - 1) * 128 + j;
;     BF8 t; t.q = make_uint4(0, 0, 0, 0);
;     if (pos >= 0) t.q = *(const uint4*)(p_proj + ((size_t)b * 8192 + pos) * INW + 640 + kvh * 64 + c * 8);
; #pragma unroll
;     for (int e = 0; e < 8; ++e) vT[(c * 8 + e) * VS + j] = (u16)(t.u[e >> 1] >> ((e & 1) * 16));
;   }
	v_add_u32_e32 v1, 0x200, v8
	v_ashrrev_i32_e32 v4, 3, v1
	v_add_u32_e32 v24, s7, v4
	v_cmp_lt_i32_e32 vcc, -1, v24
	v_mov_b32_e32 v1, 0
	v_mov_b32_e32 v2, 0
	v_mov_b32_e32 v3, 0
	v_mov_b32_e32 v202, 0
	v_mov_b32_e32 v203, 0
	v_mov_b32_e32 v204, 0
	v_mov_b32_e32 v205, 0
	s_and_saveexec_b64 s[0:1], vcc
	s_cbranch_execz .LBB0_331
	v_lshl_add_u64 v[0:1], s[38:39], 0, v[24:25]
	v_mad_u64_u32 v[2:3], s[8:9], v0, s60, v[26:27]
	v_mad_i32_i24 v3, v1, s60, v3
	s_lshl_b32 s40, s4, 1
	v_lshl_add_u64 v[0:1], v[2:3], 0, s[40:41]
	v_mov_b32_e32 v7, v25
	v_lshl_add_u64 v[0:1], v[0:1], 0, v[6:7]
	v_add_co_u32_e32 v0, vcc, 0x8140000, v0
	s_nop 1
	v_addc_co_u32_e32 v1, vcc, 0, v1, vcc
	global_load_dwordx4 v[202:205], v[0:1], off offset:1280
.LBB0_331:
	s_or_b64 exec, exec, s[0:1]
	v_lshl_add_u32 v4, v4, 1, v9


; __device__ void attn_prompt_item(const P& p, int item, u16* vT) {
;     ...
;   for (int i = 0; i < 8; ++i) {
;     int id = tid + i * 256, j = id >> 3, c = id & 7;
;     int pos = (n - 1) * 128 + j;
;     BF8 t; t.q = make_uint4(0, 0, 0, 0);
;     if (pos >= 0) t.q = *(const uint4*)(p_proj + ((size_t)b * 8192 + pos) * INW + 640 + kvh * 64 + c * 8);
; #pragma unroll
;     for (int e = 0; e < 8; ++e) vT[(c * 8 + e) * VS + j] = (u16)(t.u[e >> 1] >> ((e & 1) * 16));
;   }
	v_add_u32_e32 v0, 0x300, v8
	v_ashrrev_i32_e32 v1, 3, v0
	v_add_u32_e32 v24, s7, v1
	v_cmp_lt_i32_e32 vcc, -1, v24
	v_mov_b32_e32 v0, 0
	v_mov_b32_e32 v2, 0
	v_mov_b32_e32 v3, 0
	v_mov_b32_e32 v4, 0
	v_mov_b32_e32 v5, 0
	v_mov_b32_e32 v206, 0
	v_mov_b32_e32 v207, 0
	v_mov_b32_e32 v208, 0
	v_mov_b32_e32 v209, 0
	s_and_saveexec_b64 s[0:1], vcc
	s_cbranch_execz .LBB0_333
	v_lshl_add_u64 v[2:3], s[38:39], 0, v[24:25]
	v_mad_u64_u32 v[4:5], s[8:9], v2, s60, v[26:27]
	v_mad_i32_i24 v5, v3, s60, v5
	s_lshl_b32 s40, s4, 1
	v_lshl_add_u64 v[2:3], v[4:5], 0, s[40:41]
	v_mov_b32_e32 v7, v25
	v_lshl_add_u64 v[2:3], v[2:3], 0, v[6:7]
	v_add_co_u32_e32 v2, vcc, 0x8140000, v2
	s_nop 1
	v_addc_co_u32_e32 v3, vcc, 0, v3, vcc
	global_load_dwordx4 v[206:209], v[2:3], off offset:1280
.LBB0_333:
	s_or_b64 exec, exec, s[0:1]
	v_lshl_add_u32 v1, v1, 1, v9


; __device__ void attn_prompt_item(const P& p, int item, u16* vT) {
;     ...
;   for (int i = 0; i < 8; ++i) {
;     int id = tid + i * 256, j = id >> 3, c = id & 7;
;     int pos = (n - 1) * 128 + j;
;     BF8 t; t.q = make_uint4(0, 0, 0, 0);
;     if (pos >= 0) t.q = *(const uint4*)(p_proj + ((size_t)b * 8192 + pos) * INW + 640 + kvh * 64 + c * 8);
; #pragma unroll
;     for (int e = 0; e < 8; ++e) vT[(c * 8 + e) * VS + j] = (u16)(t.u[e >> 1] >> ((e & 1) * 16));
;   }
	v_add_u32_e32 v1, 0x400, v8
	v_ashrrev_i32_e32 v4, 3, v1
	v_add_u32_e32 v24, s7, v4
	v_cmp_lt_i32_e32 vcc, -1, v24
	v_mov_b32_e32 v1, 0
	v_mov_b32_e32 v2, 0
	v_mov_b32_e32 v3, 0
	v_mov_b32_e32 v210, 0
	v_mov_b32_e32 v211, 0
	v_mov_b32_e32 v212, 0
	v_mov_b32_e32 v213, 0
	s_and_saveexec_b64 s[0:1], vcc
	s_cbranch_execz .LBB0_335
	v_lshl_add_u64 v[0:1], s[38:39], 0, v[24:25]
	v_mad_u64_u32 v[2:3], s[8:9], v0, s60, v[26:27]
	v_mad_i32_i24 v3, v1, s60, v3
	s_lshl_b32 s40, s4, 1
	v_lshl_add_u64 v[0:1], v[2:3], 0, s[40:41]
	v_mov_b32_e32 v7, v25
	v_lshl_add_u64 v[0:1], v[0:1], 0, v[6:7]
	v_add_co_u32_e32 v0, vcc, 0x8140000, v0
	s_nop 1
	v_addc_co_u32_e32 v1, vcc, 0, v1, vcc
	global_load_dwordx4 v[210:213], v[0:1], off offset:1280
.LBB0_335:
	s_or_b64 exec, exec, s[0:1]
	v_lshl_add_u32 v4, v4, 1, v9


; __device__ void attn_prompt_item(const P& p, int item, u16* vT) {
;     ...
;   for (int i = 0; i < 8; ++i) {
;     int id = tid + i * 256, j = id >> 3, c = id & 7;
;     int pos = (n - 1) * 128 + j;
;     BF8 t; t.q = make_uint4(0, 0, 0, 0);
;     if (pos >= 0) t.q = *(const uint4*)(p_proj + ((size_t)b * 8192 + pos) * INW + 640 + kvh * 64 + c * 8);
; #pragma unroll
;     for (int e = 0; e < 8; ++e) vT[(c * 8 + e) * VS + j] = (u16)(t.u[e >> 1] >> ((e & 1) * 16));
;   }
	v_add_u32_e32 v0, 0x500, v8
	v_ashrrev_i32_e32 v1, 3, v0
	v_add_u32_e32 v24, s7, v1
	v_cmp_lt_i32_e32 vcc, -1, v24
	v_mov_b32_e32 v0, 0
	v_mov_b32_e32 v2, 0
	v_mov_b32_e32 v3, 0
	v_mov_b32_e32 v4, 0
	v_mov_b32_e32 v5, 0
	v_mov_b32_e32 v214, 0
	v_mov_b32_e32 v215, 0
	v_mov_b32_e32 v216, 0
	v_mov_b32_e32 v217, 0
	s_and_saveexec_b64 s[0:1], vcc
	s_cbranch_execz .LBB0_337
	v_lshl_add_u64 v[2:3], s[38:39], 0, v[24:25]
	v_mad_u64_u32 v[4:5], s[8:9], v2, s60, v[26:27]
	v_mad_i32_i24 v5, v3, s60, v5
	s_lshl_b32 s40, s4, 1
	v_lshl_add_u64 v[2:3], v[4:5], 0, s[40:41]
	v_mov_b32_e32 v7, v25
	v_lshl_add_u64 v[2:3], v[2:3], 0, v[6:7]
	v_add_co_u32_e32 v2, vcc, 0x8140000, v2
	s_nop 1
	v_addc_co_u32_e32 v3, vcc, 0, v3, vcc
	global_load_dwordx4 v[214:217], v[2:3], off offset:1280
.LBB0_337:
	s_or_b64 exec, exec, s[0:1]
	v_lshl_add_u32 v1, v1, 1, v9


; __device__ void attn_prompt_item(const P& p, int item, u16* vT) {
;     ...
;   for (int i = 0; i < 8; ++i) {
;     int id = tid + i * 256, j = id >> 3, c = id & 7;
;     int pos = (n - 1) * 128 + j;
;     BF8 t; t.q = make_uint4(0, 0, 0, 0);
;     if (pos >= 0) t.q = *(const uint4*)(p_proj + ((size_t)b * 8192 + pos) * INW + 640 + kvh * 64 + c * 8);
; #pragma unroll
;     for (int e = 0; e < 8; ++e) vT[(c * 8 + e) * VS + j] = (u16)(t.u[e >> 1] >> ((e & 1) * 16));
;   }
	v_add_u32_e32 v1, 0x600, v8
	v_ashrrev_i32_e32 v4, 3, v1
	v_add_u32_e32 v24, s7, v4
	v_cmp_lt_i32_e32 vcc, -1, v24
	v_mov_b32_e32 v1, 0
	v_mov_b32_e32 v2, 0
	v_mov_b32_e32 v3, 0
	v_mov_b32_e32 v222, 0
	v_mov_b32_e32 v223, 0
	v_mov_b32_e32 v224, 0
	v_mov_b32_e32 v225, 0
	s_and_saveexec_b64 s[0:1], vcc
	s_cbranch_execz .LBB0_339
	v_lshl_add_u64 v[0:1], s[38:39], 0, v[24:25]
	v_mad_u64_u32 v[2:3], s[8:9], v0, s60, v[26:27]
	v_mad_i32_i24 v3, v1, s60, v3
	s_lshl_b32 s40, s4, 1
	v_lshl_add_u64 v[0:1], v[2:3], 0, s[40:41]
	v_mov_b32_e32 v7, v25
	v_lshl_add_u64 v[0:1], v[0:1], 0, v[6:7]
	v_add_co_u32_e32 v0, vcc, 0x8140000, v0
	s_nop 1
	v_addc_co_u32_e32 v1, vcc, 0, v1, vcc
	global_load_dwordx4 v[222:225], v[0:1], off offset:1280
.LBB0_339:
	s_or_b64 exec, exec, s[0:1]
	v_lshl_add_u32 v4, v4, 1, v9


; __device__ void attn_prompt_item(const P& p, int item, u16* vT) {
;     ...
;   for (int i = 0; i < 8; ++i) {
;     int id = tid + i * 256, j = id >> 3, c = id & 7;
;     int pos = (n - 1) * 128 + j;
;     BF8 t; t.q = make_uint4(0, 0, 0, 0);
;     if (pos >= 0) t.q = *(const uint4*)(p_proj + ((size_t)b * 8192 + pos) * INW + 640 + kvh * 64 + c * 8);
; #pragma unroll
;     for (int e = 0; e < 8; ++e) vT[(c * 8 + e) * VS + j] = (u16)(t.u[e >> 1] >> ((e & 1) * 16));
;   }
;   if (tid < 64) {
; #pragma unroll
;     for (int e = 0; e < 24; ++e) vT[tid * VS + 256 + e] = 0;
;   }
	v_add_u32_e32 v0, 0x700, v8
	v_ashrrev_i32_e32 v4, 3, v0
	v_add_u32_e32 v24, s7, v4
	v_cmp_lt_i32_e32 vcc, -1, v24
	v_mov_b32_e32 v0, 0
	v_mov_b32_e32 v1, 0
	v_mov_b32_e32 v2, 0
	v_mov_b32_e32 v3, 0
	s_and_saveexec_b64 s[0:1], vcc
	s_cbranch_execz .LBB0_341
	v_lshl_add_u64 v[0:1], s[38:39], 0, v[24:25]
	v_mad_u64_u32 v[2:3], s[8:9], v0, s60, v[26:27]
	v_mad_i32_i24 v3, v1, s60, v3
	s_lshl_b32 s40, s4, 1
	v_lshl_add_u64 v[0:1], v[2:3], 0, s[40:41]
	v_mov_b32_e32 v7, v25
	v_lshl_add_u64 v[0:1], v[0:1], 0, v[6:7]
	v_add_co_u32_e32 v0, vcc, 0x8140000, v0
	s_nop 1
	v_addc_co_u32_e32 v1, vcc, 0, v1, vcc
	global_load_dwordx4 v[0:3], v[0:1], off offset:1280
.LBB0_341:
	s_or_b64 exec, exec, s[0:1]
	s_waitcnt vmcnt(7)
	ds_write_b16 v226, v194 offset:0
	ds_write_b16_d16_hi v226, v194 offset:560
	ds_write_b16 v226, v195 offset:1120
	ds_write_b16_d16_hi v226, v195 offset:1680
	ds_write_b16 v226, v196 offset:2240
	ds_write_b16_d16_hi v226, v196 offset:2800
	ds_write_b16 v226, v197 offset:3360
	ds_write_b16_d16_hi v226, v197 offset:3920
	s_waitcnt vmcnt(6)
	ds_write_b16 v226, v198 offset:64
	ds_write_b16_d16_hi v226, v198 offset:624
	ds_write_b16 v226, v199 offset:1184
	ds_write_b16_d16_hi v226, v199 offset:1744
	ds_write_b16 v226, v200 offset:2304
	ds_write_b16_d16_hi v226, v200 offset:2864
	ds_write_b16 v226, v201 offset:3424
	ds_write_b16_d16_hi v226, v201 offset:3984
	s_waitcnt vmcnt(5)
	ds_write_b16 v226, v202 offset:128
	ds_write_b16_d16_hi v226, v202 offset:688
	ds_write_b16 v226, v203 offset:1248
	ds_write_b16_d16_hi v226, v203 offset:1808
	ds_write_b16 v226, v204 offset:2368
	ds_write_b16_d16_hi v226, v204 offset:2928
	ds_write_b16 v226, v205 offset:3488
	ds_write_b16_d16_hi v226, v205 offset:4048
	s_waitcnt vmcnt(4)
	ds_write_b16 v226, v206 offset:192
	ds_write_b16_d16_hi v226, v206 offset:752
	ds_write_b16 v226, v207 offset:1312
	ds_write_b16_d16_hi v226, v207 offset:1872
	ds_write_b16 v226, v208 offset:2432
	ds_write_b16_d16_hi v226, v208 offset:2992
	ds_write_b16 v226, v209 offset:3552
	ds_write_b16_d16_hi v226, v209 offset:4112
	s_waitcnt vmcnt(3)
	ds_write_b16 v226, v210 offset:256
	ds_write_b16_d16_hi v226, v210 offset:816
	ds_write_b16 v226, v211 offset:1376
	ds_write_b16_d16_hi v226, v211 offset:1936
	ds_write_b16 v226, v212 offset:2496
	ds_write_b16_d16_hi v226, v212 offset:3056
	ds_write_b16 v226, v213 offset:3616
	ds_write_b16_d16_hi v226, v213 offset:4176
	s_waitcnt vmcnt(2)
	ds_write_b16 v226, v214 offset:320
	ds_write_b16_d16_hi v226, v214 offset:880
	ds_write_b16 v226, v215 offset:1440
	ds_write_b16_d16_hi v226, v215 offset:2000
	ds_write_b16 v226, v216 offset:2560
	ds_write_b16_d16_hi v226, v216 offset:3120
	ds_write_b16 v226, v217 offset:3680
	ds_write_b16_d16_hi v226, v217 offset:4240
	s_waitcnt vmcnt(1)
	ds_write_b16 v226, v222 offset:384
	ds_write_b16_d16_hi v226, v222 offset:944
	ds_write_b16 v226, v223 offset:1504
	ds_write_b16_d16_hi v226, v223 offset:2064
	ds_write_b16 v226, v224 offset:2624
	ds_write_b16_d16_hi v226, v224 offset:3184
	ds_write_b16 v226, v225 offset:3744
	ds_write_b16_d16_hi v226, v225 offset:4304
	v_lshl_add_u32 v4, v4, 1, v9
	v_cmp_gt_i32_e32 vcc, 64, v8
	s_waitcnt vmcnt(0)
	ds_write_b16 v4, v0
	ds_write_b16_d16_hi v4, v0 offset:560
	ds_write_b16 v4, v1 offset:1120
	ds_write_b16_d16_hi v4, v1 offset:1680
	ds_write_b16 v4, v2 offset:2240
	ds_write_b16_d16_hi v4, v2 offset:2800
	ds_write_b16 v4, v3 offset:3360
	ds_write_b16_d16_hi v4, v3 offset:3920
	s_and_saveexec_b64 s[0:1], vcc
	s_cbranch_execz .LBB0_343
	s_mov_b32 s40, s41
	s_mov_b32 s42, s41
	s_mov_b32 s43, s41
	v_mov_b64_e32 v[2:3], s[40:41]
	v_mul_lo_u32 v0, v8, s68
	v_mov_b64_e32 v[4:5], s[42:43]
	ds_write_b128 v0, v[2:5] offset:512
	ds_write_b128 v0, v[2:5] offset:528
	ds_write_b128 v0, v[2:5] offset:544
